# k2 fox loop: 32 accumulator-init subtractions per step packed into 16 v_pk_add_f32 (same arithmetic)
# baseline (speedup 1.0000x reference)
.LBB2_47:
	s_xor_b64 s[0:1], s[96:97], -1
	s_add_i32 s88, s94, -3
	s_add_i32 s93, s90, s94
	s_cmp_le_i32 s88, s87
	s_cselect_b64 s[82:83], -1, 0
	s_and_b64 s[82:83], s[78:79], s[82:83]
	s_andn2_b64 vcc, exec, s[82:83]
	s_cbranch_vccnz .LBB2_58
	v_add_u32_e32 v34, v176, v126
	ds_read_b128 v[118:121], v34
	ds_read_b128 v[122:125], v34 offset:32
	ds_read_b128 v[186:189], v34 offset:8704
	ds_read_b128 v[190:193], v34 offset:8736
	ds_read_b128 v[194:197], v34 offset:64
	ds_read_b128 v[198:201], v34 offset:96
	ds_read_b128 v[202:205], v34 offset:8768
	ds_read_b128 v[206:209], v34 offset:8800
	ds_read_b128 v[34:37], v177
	ds_read_b128 v[38:41], v177 offset:32
	ds_read_b128 v[42:45], v177 offset:64
	ds_read_b128 v[46:49], v177 offset:96
	ds_read_b128 v[50:53], v177 offset:128
	ds_read_b128 v[54:57], v177 offset:160
	ds_read_b128 v[58:61], v177 offset:192
	ds_read_b128 v[62:65], v177 offset:224
	s_waitcnt lgkmcnt(4)
	v_pk_add_f32 v[48:49], v[184:185], v[48:49] op_sel:[1,0] op_sel_hi:[1,1] neg_lo:[1,1] neg_hi:[1,1]
	v_pk_add_f32 v[46:47], v[184:185], v[46:47] op_sel:[1,0] op_sel_hi:[1,1] neg_lo:[1,1] neg_hi:[1,1]
	v_pk_add_f32 v[44:45], v[184:185], v[44:45] op_sel:[1,0] op_sel_hi:[1,1] neg_lo:[1,1] neg_hi:[1,1]
	v_pk_add_f32 v[42:43], v[184:185], v[42:43] op_sel:[1,0] op_sel_hi:[1,1] neg_lo:[1,1] neg_hi:[1,1]
	v_pk_add_f32 v[40:41], v[184:185], v[40:41] op_sel:[1,0] op_sel_hi:[1,1] neg_lo:[1,1] neg_hi:[1,1]
	v_pk_add_f32 v[38:39], v[184:185], v[38:39] op_sel:[1,0] op_sel_hi:[1,1] neg_lo:[1,1] neg_hi:[1,1]
	v_pk_add_f32 v[36:37], v[184:185], v[36:37] op_sel:[1,0] op_sel_hi:[1,1] neg_lo:[1,1] neg_hi:[1,1]
	v_pk_add_f32 v[34:35], v[184:185], v[34:35] op_sel:[1,0] op_sel_hi:[1,1] neg_lo:[1,1] neg_hi:[1,1]
	s_waitcnt lgkmcnt(0)
	v_pk_add_f32 v[64:65], v[184:185], v[64:65] op_sel:[1,0] op_sel_hi:[1,1] neg_lo:[1,1] neg_hi:[1,1]
	v_pk_add_f32 v[62:63], v[184:185], v[62:63] op_sel:[1,0] op_sel_hi:[1,1] neg_lo:[1,1] neg_hi:[1,1]
	v_pk_add_f32 v[60:61], v[184:185], v[60:61] op_sel:[1,0] op_sel_hi:[1,1] neg_lo:[1,1] neg_hi:[1,1]
	v_pk_add_f32 v[58:59], v[184:185], v[58:59] op_sel:[1,0] op_sel_hi:[1,1] neg_lo:[1,1] neg_hi:[1,1]
	v_pk_add_f32 v[56:57], v[184:185], v[56:57] op_sel:[1,0] op_sel_hi:[1,1] neg_lo:[1,1] neg_hi:[1,1]
	v_pk_add_f32 v[54:55], v[184:185], v[54:55] op_sel:[1,0] op_sel_hi:[1,1] neg_lo:[1,1] neg_hi:[1,1]
	v_pk_add_f32 v[52:53], v[184:185], v[52:53] op_sel:[1,0] op_sel_hi:[1,1] neg_lo:[1,1] neg_hi:[1,1]
	v_pk_add_f32 v[50:51], v[184:185], v[50:51] op_sel:[1,0] op_sel_hi:[1,1] neg_lo:[1,1] neg_hi:[1,1]
	v_mfma_f32_32x32x16_bf16 v[34:49], v[118:121], v[66:69], v[34:49]
	s_nop 0
	v_mfma_f32_32x32x16_bf16 v[50:65], v[186:189], v[66:69], v[50:65]
	v_mfma_f32_32x32x16_bf16 v[34:49], v[122:125], v[70:73], v[34:49]
	ds_read_b64_tr_b16 v[122:123], v178 offset:34816
	ds_read_b64_tr_b16 v[124:125], v178 offset:37376
	ds_read_b64_tr_b16 v[120:121], v178 offset:37440
	ds_read_b64_tr_b16 v[118:119], v178 offset:34880
	v_mfma_f32_32x32x16_bf16 v[50:65], v[190:193], v[70:73], v[50:65]
	v_mfma_f32_32x32x16_bf16 v[34:49], v[194:197], v[74:77], v[34:49]
	v_mfma_f32_32x32x16_bf16 v[50:65], v[202:205], v[74:77], v[50:65]
	v_mfma_f32_32x32x16_bf16 v[34:49], v[198:201], v[78:81], v[34:49]
	v_mfma_f32_32x32x16_bf16 v[50:65], v[206:209], v[78:81], v[50:65]
	s_cmp_lg_u32 s93, 3
	s_cbranch_scc1 .LBB2_50
	s_nop 8
	v_cndmask_b32_e64 v98, v34, v238, s[6:7]
	v_cndmask_b32_e64 v50, v50, v238, s[8:9]
	v_cndmask_b32_e64 v35, v238, v35, s[10:11]
	v_cndmask_b32_e64 v34, v98, v34, s[10:11]
	v_cndmask_b32_e64 v51, v51, v238, s[12:13]
	v_cndmask_b32_e64 v36, v36, v238, s[14:15]
	v_cndmask_b32_e64 v52, v52, v238, s[16:17]
	v_cndmask_b32_e64 v37, v37, v238, s[18:19]
	v_cndmask_b32_e64 v53, v53, v238, s[20:21]
	v_cndmask_b32_e64 v38, v38, v238, s[22:23]
	v_cndmask_b32_e64 v54, v54, v238, s[24:25]
	v_cndmask_b32_e64 v39, v39, v238, s[26:27]
	v_cndmask_b32_e64 v55, v55, v238, s[28:29]
	v_cndmask_b32_e64 v40, v40, v238, s[30:31]
	v_cndmask_b32_e64 v56, v56, v238, s[34:35]
	v_cndmask_b32_e64 v41, v41, v238, s[36:37]
	v_cndmask_b32_e64 v57, v57, v238, s[38:39]
	v_cndmask_b32_e64 v42, v42, v238, s[40:41]
	v_cndmask_b32_e64 v58, v58, v238, s[42:43]
	v_cndmask_b32_e64 v43, v43, v238, s[44:45]
	v_cndmask_b32_e64 v59, v59, v238, s[46:47]
	v_cndmask_b32_e64 v44, v44, v238, s[48:49]
	v_cndmask_b32_e64 v60, v60, v238, s[50:51]
	v_cndmask_b32_e64 v45, v45, v238, s[52:53]
	v_cndmask_b32_e64 v61, v61, v238, s[54:55]
	v_cndmask_b32_e64 v46, v46, v238, s[56:57]
	v_cndmask_b32_e64 v62, v62, v238, s[58:59]
	v_cndmask_b32_e64 v47, v47, v238, s[60:61]
	v_cndmask_b32_e64 v63, v63, v238, s[62:63]
	v_cndmask_b32_e64 v48, v48, v238, s[64:65]
	v_cndmask_b32_e64 v64, v64, v238, s[66:67]
	v_cndmask_b32_e64 v49, v49, v238, s[68:69]
	v_cndmask_b32_e64 v65, v65, v238, s[70:71]

.LBB2_73:
	s_cmp_lt_i32 s88, s87
	s_cselect_b64 s[82:83], -1, 0
	s_and_b64 s[82:83], s[78:79], s[82:83]
	s_andn2_b64 vcc, exec, s[82:83]
	s_cbranch_vccnz .LBB2_84
	v_add_u32_e32 v34, v176, v126
	ds_read_b128 v[118:121], v34 offset:17408
	ds_read_b128 v[122:125], v34 offset:17440
	ds_read_b128 v[186:189], v34 offset:26112
	ds_read_b128 v[190:193], v34 offset:26144
	ds_read_b128 v[194:197], v34 offset:17472
	ds_read_b128 v[198:201], v34 offset:17504
	ds_read_b128 v[202:205], v34 offset:26176
	ds_read_b128 v[206:209], v34 offset:26208
	ds_read_b128 v[34:37], v180
	ds_read_b128 v[38:41], v180 offset:32
	ds_read_b128 v[42:45], v180 offset:64
	ds_read_b128 v[46:49], v180 offset:96
	ds_read_b128 v[50:53], v180 offset:128
	ds_read_b128 v[54:57], v180 offset:160
	ds_read_b128 v[58:61], v180 offset:192
	ds_read_b128 v[62:65], v180 offset:224
	s_waitcnt lgkmcnt(4)
	v_pk_add_f32 v[48:49], v[184:185], v[48:49] op_sel:[1,0] op_sel_hi:[1,1] neg_lo:[1,1] neg_hi:[1,1]
	v_pk_add_f32 v[46:47], v[184:185], v[46:47] op_sel:[1,0] op_sel_hi:[1,1] neg_lo:[1,1] neg_hi:[1,1]
	v_pk_add_f32 v[44:45], v[184:185], v[44:45] op_sel:[1,0] op_sel_hi:[1,1] neg_lo:[1,1] neg_hi:[1,1]
	v_pk_add_f32 v[42:43], v[184:185], v[42:43] op_sel:[1,0] op_sel_hi:[1,1] neg_lo:[1,1] neg_hi:[1,1]
	v_pk_add_f32 v[40:41], v[184:185], v[40:41] op_sel:[1,0] op_sel_hi:[1,1] neg_lo:[1,1] neg_hi:[1,1]
	v_pk_add_f32 v[38:39], v[184:185], v[38:39] op_sel:[1,0] op_sel_hi:[1,1] neg_lo:[1,1] neg_hi:[1,1]
	v_pk_add_f32 v[36:37], v[184:185], v[36:37] op_sel:[1,0] op_sel_hi:[1,1] neg_lo:[1,1] neg_hi:[1,1]
	v_pk_add_f32 v[34:35], v[184:185], v[34:35] op_sel:[1,0] op_sel_hi:[1,1] neg_lo:[1,1] neg_hi:[1,1]
	s_waitcnt lgkmcnt(0)
	v_pk_add_f32 v[64:65], v[184:185], v[64:65] op_sel:[1,0] op_sel_hi:[1,1] neg_lo:[1,1] neg_hi:[1,1]
	v_pk_add_f32 v[62:63], v[184:185], v[62:63] op_sel:[1,0] op_sel_hi:[1,1] neg_lo:[1,1] neg_hi:[1,1]
	v_pk_add_f32 v[60:61], v[184:185], v[60:61] op_sel:[1,0] op_sel_hi:[1,1] neg_lo:[1,1] neg_hi:[1,1]
	v_pk_add_f32 v[58:59], v[184:185], v[58:59] op_sel:[1,0] op_sel_hi:[1,1] neg_lo:[1,1] neg_hi:[1,1]
	v_pk_add_f32 v[56:57], v[184:185], v[56:57] op_sel:[1,0] op_sel_hi:[1,1] neg_lo:[1,1] neg_hi:[1,1]
	v_pk_add_f32 v[54:55], v[184:185], v[54:55] op_sel:[1,0] op_sel_hi:[1,1] neg_lo:[1,1] neg_hi:[1,1]
	v_pk_add_f32 v[52:53], v[184:185], v[52:53] op_sel:[1,0] op_sel_hi:[1,1] neg_lo:[1,1] neg_hi:[1,1]
	v_pk_add_f32 v[50:51], v[184:185], v[50:51] op_sel:[1,0] op_sel_hi:[1,1] neg_lo:[1,1] neg_hi:[1,1]
	v_mfma_f32_32x32x16_bf16 v[34:49], v[118:121], v[66:69], v[34:49]
	s_nop 0
	v_mfma_f32_32x32x16_bf16 v[50:65], v[186:189], v[66:69], v[50:65]
	v_mfma_f32_32x32x16_bf16 v[34:49], v[122:125], v[70:73], v[34:49]
	ds_read_b64_tr_b16 v[122:123], v178 offset:55296
	ds_read_b64_tr_b16 v[124:125], v178 offset:57856
	ds_read_b64_tr_b16 v[120:121], v178 offset:57920
	ds_read_b64_tr_b16 v[118:119], v178 offset:55360
	v_mfma_f32_32x32x16_bf16 v[50:65], v[190:193], v[70:73], v[50:65]
	v_mfma_f32_32x32x16_bf16 v[34:49], v[194:197], v[74:77], v[34:49]
	v_mfma_f32_32x32x16_bf16 v[50:65], v[202:205], v[74:77], v[50:65]
	v_mfma_f32_32x32x16_bf16 v[34:49], v[198:201], v[78:81], v[34:49]
	v_mfma_f32_32x32x16_bf16 v[50:65], v[206:209], v[78:81], v[50:65]
	s_cmp_lg_u32 s93, 2
	s_cbranch_scc1 .LBB2_76
	s_nop 8
	v_cndmask_b32_e64 v98, v34, v238, s[6:7]
	v_cndmask_b32_e64 v50, v50, v238, s[8:9]
	v_cndmask_b32_e64 v35, v238, v35, s[10:11]
	v_cndmask_b32_e64 v34, v98, v34, s[10:11]
	v_cndmask_b32_e64 v51, v51, v238, s[12:13]
	v_cndmask_b32_e64 v36, v36, v238, s[14:15]
	v_cndmask_b32_e64 v52, v52, v238, s[16:17]
	v_cndmask_b32_e64 v37, v37, v238, s[18:19]
	v_cndmask_b32_e64 v53, v53, v238, s[20:21]
	v_cndmask_b32_e64 v38, v38, v238, s[22:23]
	v_cndmask_b32_e64 v54, v54, v238, s[24:25]
	v_cndmask_b32_e64 v39, v39, v238, s[26:27]
	v_cndmask_b32_e64 v55, v55, v238, s[28:29]
	v_cndmask_b32_e64 v40, v40, v238, s[30:31]
	v_cndmask_b32_e64 v56, v56, v238, s[34:35]
	v_cndmask_b32_e64 v41, v41, v238, s[36:37]
	v_cndmask_b32_e64 v57, v57, v238, s[38:39]
	v_cndmask_b32_e64 v42, v42, v238, s[40:41]
	v_cndmask_b32_e64 v58, v58, v238, s[42:43]
	v_cndmask_b32_e64 v43, v43, v238, s[44:45]
	v_cndmask_b32_e64 v59, v59, v238, s[46:47]
	v_cndmask_b32_e64 v44, v44, v238, s[48:49]
	v_cndmask_b32_e64 v60, v60, v238, s[50:51]
	v_cndmask_b32_e64 v45, v45, v238, s[52:53]
	v_cndmask_b32_e64 v61, v61, v238, s[54:55]
	v_cndmask_b32_e64 v46, v46, v238, s[56:57]
	v_cndmask_b32_e64 v62, v62, v238, s[58:59]
	v_cndmask_b32_e64 v47, v47, v238, s[60:61]
	v_cndmask_b32_e64 v63, v63, v238, s[62:63]
	v_cndmask_b32_e64 v48, v48, v238, s[64:65]
	v_cndmask_b32_e64 v64, v64, v238, s[66:67]
	v_cndmask_b32_e64 v49, v49, v238, s[68:69]
	v_cndmask_b32_e64 v65, v65, v238, s[70:71]
